# residual/pre-norm phases hand-rewritten (DPP reductions, 1 barrier per step, counted vmcnt double-buffer), region sizes padded so hot loops keep baseline addresses
# speedup vs baseline: 1.0051x; 1.0051x over previous
; __device__ __forceinline__ void phase_residual(const Args& A, int li, LAS unsigned char* lds, int tid, int wid, int lane) {
;     ...
;         if (nxt) {
; #pragma unroll
;             for (int r = 0; r < 8; ++r) { float s = (xv[r][0] * xv[r][0] + xv[r][1] * xv[r][1]) + (xv[r][2] * xv[r][2] + xv[r][3] * xv[r][3]); s = wave_sum(s); if (lane == 0) part[r * 8 + wid] = s; }
;             __syncthreads();
.Lr1_nopf1:
	v_add_f32_e32 v162, 1.0, v126
	v_add_f32_e32 v163, 1.0, v127
	v_add_f32_e32 v164, 1.0, v128
	v_add_f32_e32 v165, 1.0, v129
	v_mul_f32_e32 v162, v162, v134
	v_mul_f32_e32 v163, v163, v135
	v_mul_f32_e32 v164, v164, v136
	v_mul_f32_e32 v165, v165, v137
	v_mul_f32_e32 v166, v66, v66
	v_mul_f32_e32 v167, v70, v70
	v_mul_f32_e32 v168, v74, v74
	v_mul_f32_e32 v169, v78, v78
	v_mul_f32_e32 v170, v82, v82
	v_mul_f32_e32 v171, v86, v86
	v_mul_f32_e32 v172, v90, v90
	v_mul_f32_e32 v173, v94, v94
	v_fmac_f32_e32 v166, v67, v67
	v_fmac_f32_e32 v167, v71, v71
	v_fmac_f32_e32 v168, v75, v75
	v_fmac_f32_e32 v169, v79, v79
	v_fmac_f32_e32 v170, v83, v83
	v_fmac_f32_e32 v171, v87, v87
	v_fmac_f32_e32 v172, v91, v91
	v_fmac_f32_e32 v173, v95, v95
	v_fmac_f32_e32 v166, v68, v68
	v_fmac_f32_e32 v167, v72, v72
	v_fmac_f32_e32 v168, v76, v76
	v_fmac_f32_e32 v169, v80, v80
	v_fmac_f32_e32 v170, v84, v84
	v_fmac_f32_e32 v171, v88, v88
	v_fmac_f32_e32 v172, v92, v92
	v_fmac_f32_e32 v173, v96, v96
	v_fmac_f32_e32 v166, v69, v69
	v_fmac_f32_e32 v167, v73, v73
	v_fmac_f32_e32 v168, v77, v77
	v_fmac_f32_e32 v169, v81, v81
	v_fmac_f32_e32 v170, v85, v85
	v_fmac_f32_e32 v171, v89, v89
	v_fmac_f32_e32 v172, v93, v93
	v_fmac_f32_e32 v173, v97, v97
	v_add_f32_dpp v166, v166, v166 quad_perm:[1,0,3,2] row_mask:0xf bank_mask:0xf bound_ctrl:1
	v_add_f32_dpp v167, v167, v167 quad_perm:[1,0,3,2] row_mask:0xf bank_mask:0xf bound_ctrl:1
	v_add_f32_dpp v168, v168, v168 quad_perm:[1,0,3,2] row_mask:0xf bank_mask:0xf bound_ctrl:1
	v_add_f32_dpp v169, v169, v169 quad_perm:[1,0,3,2] row_mask:0xf bank_mask:0xf bound_ctrl:1
	v_add_f32_dpp v170, v170, v170 quad_perm:[1,0,3,2] row_mask:0xf bank_mask:0xf bound_ctrl:1
	v_add_f32_dpp v171, v171, v171 quad_perm:[1,0,3,2] row_mask:0xf bank_mask:0xf bound_ctrl:1
	v_add_f32_dpp v172, v172, v172 quad_perm:[1,0,3,2] row_mask:0xf bank_mask:0xf bound_ctrl:1
	v_add_f32_dpp v173, v173, v173 quad_perm:[1,0,3,2] row_mask:0xf bank_mask:0xf bound_ctrl:1
	v_add_f32_dpp v166, v166, v166 quad_perm:[2,3,0,1] row_mask:0xf bank_mask:0xf bound_ctrl:1
	v_add_f32_dpp v167, v167, v167 quad_perm:[2,3,0,1] row_mask:0xf bank_mask:0xf bound_ctrl:1
	v_add_f32_dpp v168, v168, v168 quad_perm:[2,3,0,1] row_mask:0xf bank_mask:0xf bound_ctrl:1
	v_add_f32_dpp v169, v169, v169 quad_perm:[2,3,0,1] row_mask:0xf bank_mask:0xf bound_ctrl:1
	v_add_f32_dpp v170, v170, v170 quad_perm:[2,3,0,1] row_mask:0xf bank_mask:0xf bound_ctrl:1
	v_add_f32_dpp v171, v171, v171 quad_perm:[2,3,0,1] row_mask:0xf bank_mask:0xf bound_ctrl:1
	v_add_f32_dpp v172, v172, v172 quad_perm:[2,3,0,1] row_mask:0xf bank_mask:0xf bound_ctrl:1
	v_add_f32_dpp v173, v173, v173 quad_perm:[2,3,0,1] row_mask:0xf bank_mask:0xf bound_ctrl:1
	v_add_f32_dpp v166, v166, v166 row_half_mirror row_mask:0xf bank_mask:0xf bound_ctrl:1
	v_add_f32_dpp v167, v167, v167 row_half_mirror row_mask:0xf bank_mask:0xf bound_ctrl:1
	v_add_f32_dpp v168, v168, v168 row_half_mirror row_mask:0xf bank_mask:0xf bound_ctrl:1
	v_add_f32_dpp v169, v169, v169 row_half_mirror row_mask:0xf bank_mask:0xf bound_ctrl:1
	v_add_f32_dpp v170, v170, v170 row_half_mirror row_mask:0xf bank_mask:0xf bound_ctrl:1
	v_add_f32_dpp v171, v171, v171 row_half_mirror row_mask:0xf bank_mask:0xf bound_ctrl:1
	v_add_f32_dpp v172, v172, v172 row_half_mirror row_mask:0xf bank_mask:0xf bound_ctrl:1
	v_add_f32_dpp v173, v173, v173 row_half_mirror row_mask:0xf bank_mask:0xf bound_ctrl:1
	v_add_f32_dpp v166, v166, v166 row_mirror row_mask:0xf bank_mask:0xf bound_ctrl:1
	v_add_f32_dpp v167, v167, v167 row_mirror row_mask:0xf bank_mask:0xf bound_ctrl:1
	v_add_f32_dpp v168, v168, v168 row_mirror row_mask:0xf bank_mask:0xf bound_ctrl:1
	v_add_f32_dpp v169, v169, v169 row_mirror row_mask:0xf bank_mask:0xf bound_ctrl:1
	v_add_f32_dpp v170, v170, v170 row_mirror row_mask:0xf bank_mask:0xf bound_ctrl:1
	v_add_f32_dpp v171, v171, v171 row_mirror row_mask:0xf bank_mask:0xf bound_ctrl:1
	v_add_f32_dpp v172, v172, v172 row_mirror row_mask:0xf bank_mask:0xf bound_ctrl:1
	v_add_f32_dpp v173, v173, v173 row_mirror row_mask:0xf bank_mask:0xf bound_ctrl:1
	v_add_f32_dpp v166, v166, v166 row_bcast:15 row_mask:0xa bank_mask:0xf
	v_add_f32_dpp v167, v167, v167 row_bcast:15 row_mask:0xa bank_mask:0xf
	v_add_f32_dpp v168, v168, v168 row_bcast:15 row_mask:0xa bank_mask:0xf
	v_add_f32_dpp v169, v169, v169 row_bcast:15 row_mask:0xa bank_mask:0xf
	v_add_f32_dpp v170, v170, v170 row_bcast:15 row_mask:0xa bank_mask:0xf
	v_add_f32_dpp v171, v171, v171 row_bcast:15 row_mask:0xa bank_mask:0xf
	v_add_f32_dpp v172, v172, v172 row_bcast:15 row_mask:0xa bank_mask:0xf
	v_add_f32_dpp v173, v173, v173 row_bcast:15 row_mask:0xa bank_mask:0xf
	v_add_f32_dpp v166, v166, v166 row_bcast:31 row_mask:0xc bank_mask:0xf
	v_add_f32_dpp v167, v167, v167 row_bcast:31 row_mask:0xc bank_mask:0xf
	v_add_f32_dpp v168, v168, v168 row_bcast:31 row_mask:0xc bank_mask:0xf
	v_add_f32_dpp v169, v169, v169 row_bcast:31 row_mask:0xc bank_mask:0xf
	v_add_f32_dpp v170, v170, v170 row_bcast:31 row_mask:0xc bank_mask:0xf
	v_add_f32_dpp v171, v171, v171 row_bcast:31 row_mask:0xc bank_mask:0xf
	v_add_f32_dpp v172, v172, v172 row_bcast:31 row_mask:0xc bank_mask:0xf
	v_add_f32_dpp v173, v173, v173 row_bcast:31 row_mask:0xc bank_mask:0xf
	s_nop 1
	s_brev_b64 exec, 1
	s_nop 1
	ds_write_b32 v156, v166 offset:256
	ds_write_b32 v156, v167 offset:288
	ds_write_b32 v156, v168 offset:320
	ds_write_b32 v156, v169 offset:352
	ds_write_b32 v156, v170 offset:384
	ds_write_b32 v156, v171 offset:416
	ds_write_b32 v156, v172 offset:448
	ds_write_b32 v156, v173 offset:480
	s_mov_b64 exec, -1
	s_waitcnt lgkmcnt(0)
	s_barrier
; __device__ __forceinline__ unsigned pk2(float lo, float hi) { f32x2 v = {lo, hi}; bf16x2_t b = __builtin_convertvector(v, bf16x2_t); return __builtin_bit_cast(unsigned, b); }
; __device__ __forceinline__ void phase_residual(const Args& A, int li, LAS unsigned char* lds, int tid, int wid, int lane) {
;     ...
; #pragma unroll
;             for (int r = 0; r < 8; ++r) { float s = 0.f;
; #pragma unroll
;                 for (int w = 0; w < 8; ++w) s += part[r * 8 + w];
;                 const float rs = __builtin_amdgcn_rsqf(s * (1.0f / DM) + EPS);
;                 const f32x4 hv = (xv[r] * rs) * preg * sc1 + sh;
;                 u32x2 o; o.x = pk2(hv[0], hv[1]); o.y = pk2(hv[2], hv[3]);
;                 *(u32x2*)(H + (size_t)(r0 + r) * DM + c0) = o; }
;         }
;         __syncthreads();
;     }
	ds_read_b32 v186, v155 offset:256
	s_waitcnt lgkmcnt(0)
	s_nop 1
	v_add_f32_dpp v186, v186, v186 quad_perm:[1,0,3,2] row_mask:0xf bank_mask:0xf bound_ctrl:1
	s_nop 1
	v_add_f32_dpp v186, v186, v186 quad_perm:[2,3,0,1] row_mask:0xf bank_mask:0xf bound_ctrl:1
	s_nop 1
	v_add_f32_dpp v186, v186, v186 row_half_mirror row_mask:0xf bank_mask:0xf bound_ctrl:1
	v_fmamk_f32 v186, v186, 0x3a000000, v205
	v_rsq_f32_e32 v186, v186
	s_nop 1
	v_readlane_b32 s24, v186, 0
	v_readlane_b32 s25, v186, 8
	v_readlane_b32 s26, v186, 16
	v_readlane_b32 s27, v186, 24
	v_readlane_b32 s28, v186, 32
	v_readlane_b32 s29, v186, 40
	v_readlane_b32 s30, v186, 48
	v_readlane_b32 s31, v186, 56
	s_nop 1
	v_mul_f32_e32 v174, s24, v66
	v_mul_f32_e32 v175, s24, v67
	v_mul_f32_e32 v176, s24, v68
	v_mul_f32_e32 v177, s24, v69
	v_fma_f32 v174, v174, v162, v122
	v_fma_f32 v175, v175, v163, v123
	v_fma_f32 v176, v176, v164, v124
	v_fma_f32 v177, v177, v165, v125
	v_cvt_pk_bf16_f32 v182, v174, v175
	v_cvt_pk_bf16_f32 v183, v176, v177
	global_store_dwordx2 v146, v[182:183], s[10:11]
	v_mul_f32_e32 v178, s25, v70
	v_mul_f32_e32 v179, s25, v71
	v_mul_f32_e32 v180, s25, v72
	v_mul_f32_e32 v181, s25, v73
	v_fma_f32 v178, v178, v162, v122
	v_fma_f32 v179, v179, v163, v123
	v_fma_f32 v180, v180, v164, v124
	v_fma_f32 v181, v181, v165, v125
	v_cvt_pk_bf16_f32 v184, v178, v179
	v_cvt_pk_bf16_f32 v185, v180, v181
	global_store_dwordx2 v147, v[184:185], s[10:11]
	v_mul_f32_e32 v174, s26, v74
	v_mul_f32_e32 v175, s26, v75
	v_mul_f32_e32 v176, s26, v76
	v_mul_f32_e32 v177, s26, v77
	v_fma_f32 v174, v174, v162, v122
	v_fma_f32 v175, v175, v163, v123
	v_fma_f32 v176, v176, v164, v124
	v_fma_f32 v177, v177, v165, v125
	v_cvt_pk_bf16_f32 v182, v174, v175
	v_cvt_pk_bf16_f32 v183, v176, v177
	global_store_dwordx2 v148, v[182:183], s[10:11]
	v_mul_f32_e32 v178, s27, v78
	v_mul_f32_e32 v179, s27, v79
	v_mul_f32_e32 v180, s27, v80
	v_mul_f32_e32 v181, s27, v81
	v_fma_f32 v178, v178, v162, v122
	v_fma_f32 v179, v179, v163, v123
	v_fma_f32 v180, v180, v164, v124
	v_fma_f32 v181, v181, v165, v125
	v_cvt_pk_bf16_f32 v184, v178, v179
	v_cvt_pk_bf16_f32 v185, v180, v181
	global_store_dwordx2 v149, v[184:185], s[10:11]
	v_mul_f32_e32 v174, s28, v82
	v_mul_f32_e32 v175, s28, v83
	v_mul_f32_e32 v176, s28, v84
	v_mul_f32_e32 v177, s28, v85
	v_fma_f32 v174, v174, v162, v122
	v_fma_f32 v175, v175, v163, v123
	v_fma_f32 v176, v176, v164, v124
	v_fma_f32 v177, v177, v165, v125
	v_cvt_pk_bf16_f32 v182, v174, v175
	v_cvt_pk_bf16_f32 v183, v176, v177
	global_store_dwordx2 v150, v[182:183], s[10:11]
	v_mul_f32_e32 v178, s29, v86
	v_mul_f32_e32 v179, s29, v87
	v_mul_f32_e32 v180, s29, v88
	v_mul_f32_e32 v181, s29, v89
	v_fma_f32 v178, v178, v162, v122
	v_fma_f32 v179, v179, v163, v123
	v_fma_f32 v180, v180, v164, v124
	v_fma_f32 v181, v181, v165, v125
	v_cvt_pk_bf16_f32 v184, v178, v179
	v_cvt_pk_bf16_f32 v185, v180, v181
	global_store_dwordx2 v151, v[184:185], s[10:11]
	v_mul_f32_e32 v174, s30, v90
	v_mul_f32_e32 v175, s30, v91
	v_mul_f32_e32 v176, s30, v92
	v_mul_f32_e32 v177, s30, v93
	v_fma_f32 v174, v174, v162, v122
	v_fma_f32 v175, v175, v163, v123
	v_fma_f32 v176, v176, v164, v124
	v_fma_f32 v177, v177, v165, v125
	v_cvt_pk_bf16_f32 v182, v174, v175
	v_cvt_pk_bf16_f32 v183, v176, v177
	global_store_dwordx2 v152, v[182:183], s[10:11]
	v_mul_f32_e32 v178, s31, v94
	v_mul_f32_e32 v179, s31, v95
	v_mul_f32_e32 v180, s31, v96
	v_mul_f32_e32 v181, s31, v97
	v_fma_f32 v178, v178, v162, v122
	v_fma_f32 v179, v179, v163, v123
	v_fma_f32 v180, v180, v164, v124
	v_fma_f32 v181, v181, v165, v125
	v_cvt_pk_bf16_f32 v184, v178, v179
	v_cvt_pk_bf16_f32 v185, v180, v181
	global_store_dwordx2 v153, v[184:185], s[10:11]
	s_lshl_b32 s22, s86, 15
	s_add_u32 s10, s10, s22
	s_addc_u32 s11, s11, 0
	s_add_i32 s20, s20, s86
	s_cmpk_lt_u32 s20, 0x1000
	s_cbranch_scc0 .LBB0_38
	s_branch .Lr1_body0
	s_nop 0
	s_nop 0
	s_nop 0
	s_nop 0
	s_nop 0
	s_nop 0
	s_nop 0
	s_nop 0
	s_nop 0
	s_nop 0
	s_nop 0
	s_nop 0
	s_nop 0
	s_nop 0
	s_nop 0
	s_nop 0
	s_nop 0
	s_nop 0
	s_nop 0
	s_nop 0
	s_nop 0
	s_nop 0
	s_nop 0
	s_nop 0
	s_nop 0
	s_nop 0
	s_nop 0
	s_nop 0
	s_nop 0
	s_nop 0
	s_nop 0
	s_nop 0
	s_nop 0
	s_nop 0
	s_nop 0
	s_nop 0
	s_nop 0
	s_nop 0
	s_nop 0
	s_nop 0
	s_nop 0
	s_nop 0
	s_nop 0
	s_nop 0
	s_nop 0
	s_nop 0
	s_nop 0
	s_nop 0
	s_nop 0
	s_nop 0
	s_nop 0
	s_nop 0
	s_nop 0
	s_nop 0
	s_nop 0
	s_nop 0
	s_nop 0

; __device__ __forceinline__ void phase_residual(const Args& A, int li, LAS unsigned char* lds, int tid, int wid, int lane) {
;     ...
;         if (upd) {
;             { float s = (lane < 32) ? staty[(size_t)(r0 + wid) * 32 + lane] : 0.f; s = wave_sum(s); if (lane == 0) rsY[wid] = __builtin_amdgcn_rsqf(s * (1.0f / DM) + EPS); }
;             __syncthreads();
; #pragma unroll
;             for (int r = 0; r < 8; ++r) { const float rs = rsY[r]; const f32x4 y = {bf_lo(yv[r].x), bf_hi(yv[r].x), bf_lo(yv[r].y), bf_hi(yv[r].y)};
;                 xv[r] = xv[r] + gate * (y * rs) * postg;
;                 *(f32x4*)(xout + (size_t)(r0 + r) * DM + c0) = xv[r]; }
;         }
.Lr2c_nopf1:
	v_add_f32_e32 v186, v114, v115
	v_add_f32_e32 v187, v116, v117
	v_add_f32_e32 v186, v186, v187
	s_nop 1
	v_add_f32_dpp v186, v186, v186 quad_perm:[1,0,3,2] row_mask:0xf bank_mask:0xf bound_ctrl:1
	s_nop 1
	v_add_f32_dpp v186, v186, v186 quad_perm:[2,3,0,1] row_mask:0xf bank_mask:0xf bound_ctrl:1
	s_nop 1
	v_add_f32_dpp v186, v186, v186 row_half_mirror row_mask:0xf bank_mask:0xf bound_ctrl:1
	v_fmamk_f32 v186, v186, 0x3a000000, v205
	v_rsq_f32_e32 v186, v186
	s_nop 1
	v_readlane_b32 s24, v186, 0
	v_readlane_b32 s25, v186, 8
	v_readlane_b32 s26, v186, 16
	v_readlane_b32 s27, v186, 24
	v_readlane_b32 s28, v186, 32
	v_readlane_b32 s29, v186, 40
	v_readlane_b32 s30, v186, 48
	v_readlane_b32 s31, v186, 56
	s_nop 1
	v_mul_f32_e32 v158, v118, v130
	v_mul_f32_e32 v159, v119, v131
	v_mul_f32_e32 v160, v120, v132
	v_mul_f32_e32 v161, v121, v133
	v_lshlrev_b32_e32 v174, 16, v98
	v_and_b32_e32 v175, 0xffff0000, v98
	v_lshlrev_b32_e32 v176, 16, v99
	v_and_b32_e32 v177, 0xffff0000, v99
	v_mul_f32_e32 v174, s24, v174
	v_mul_f32_e32 v175, s24, v175
	v_mul_f32_e32 v176, s24, v176
	v_mul_f32_e32 v177, s24, v177
	v_fmac_f32_e32 v66, v174, v158
	v_fmac_f32_e32 v67, v175, v159
	v_fmac_f32_e32 v68, v176, v160
	v_fmac_f32_e32 v69, v177, v161
	global_store_dwordx4 v138, v[66:69], s[6:7]
	v_lshlrev_b32_e32 v178, 16, v100
	v_and_b32_e32 v179, 0xffff0000, v100
	v_lshlrev_b32_e32 v180, 16, v101
	v_and_b32_e32 v181, 0xffff0000, v101
	v_mul_f32_e32 v178, s25, v178
	v_mul_f32_e32 v179, s25, v179
	v_mul_f32_e32 v180, s25, v180
	v_mul_f32_e32 v181, s25, v181
	v_fmac_f32_e32 v70, v178, v158
	v_fmac_f32_e32 v71, v179, v159
	v_fmac_f32_e32 v72, v180, v160
	v_fmac_f32_e32 v73, v181, v161
	global_store_dwordx4 v139, v[70:73], s[6:7]
	v_lshlrev_b32_e32 v174, 16, v102
	v_and_b32_e32 v175, 0xffff0000, v102
	v_lshlrev_b32_e32 v176, 16, v103
	v_and_b32_e32 v177, 0xffff0000, v103
	v_mul_f32_e32 v174, s26, v174
	v_mul_f32_e32 v175, s26, v175
	v_mul_f32_e32 v176, s26, v176
	v_mul_f32_e32 v177, s26, v177
	v_fmac_f32_e32 v74, v174, v158
	v_fmac_f32_e32 v75, v175, v159
	v_fmac_f32_e32 v76, v176, v160
	v_fmac_f32_e32 v77, v177, v161
	global_store_dwordx4 v140, v[74:77], s[6:7]
	v_lshlrev_b32_e32 v178, 16, v104
	v_and_b32_e32 v179, 0xffff0000, v104
	v_lshlrev_b32_e32 v180, 16, v105
	v_and_b32_e32 v181, 0xffff0000, v105
	v_mul_f32_e32 v178, s27, v178
	v_mul_f32_e32 v179, s27, v179
	v_mul_f32_e32 v180, s27, v180
	v_mul_f32_e32 v181, s27, v181
	v_fmac_f32_e32 v78, v178, v158
	v_fmac_f32_e32 v79, v179, v159
	v_fmac_f32_e32 v80, v180, v160
	v_fmac_f32_e32 v81, v181, v161
	global_store_dwordx4 v141, v[78:81], s[6:7]
	v_lshlrev_b32_e32 v174, 16, v106
	v_and_b32_e32 v175, 0xffff0000, v106
	v_lshlrev_b32_e32 v176, 16, v107
	v_and_b32_e32 v177, 0xffff0000, v107
	v_mul_f32_e32 v174, s28, v174
	v_mul_f32_e32 v175, s28, v175
	v_mul_f32_e32 v176, s28, v176
	v_mul_f32_e32 v177, s28, v177
	v_fmac_f32_e32 v82, v174, v158
	v_fmac_f32_e32 v83, v175, v159
	v_fmac_f32_e32 v84, v176, v160
	v_fmac_f32_e32 v85, v177, v161
	global_store_dwordx4 v142, v[82:85], s[6:7]
	v_lshlrev_b32_e32 v178, 16, v108
	v_and_b32_e32 v179, 0xffff0000, v108
	v_lshlrev_b32_e32 v180, 16, v109
	v_and_b32_e32 v181, 0xffff0000, v109
	v_mul_f32_e32 v178, s29, v178
	v_mul_f32_e32 v179, s29, v179
	v_mul_f32_e32 v180, s29, v180
	v_mul_f32_e32 v181, s29, v181
	v_fmac_f32_e32 v86, v178, v158
	v_fmac_f32_e32 v87, v179, v159
	v_fmac_f32_e32 v88, v180, v160
	v_fmac_f32_e32 v89, v181, v161
	global_store_dwordx4 v143, v[86:89], s[6:7]
	v_lshlrev_b32_e32 v174, 16, v110
	v_and_b32_e32 v175, 0xffff0000, v110
	v_lshlrev_b32_e32 v176, 16, v111
	v_and_b32_e32 v177, 0xffff0000, v111
	v_mul_f32_e32 v174, s30, v174
	v_mul_f32_e32 v175, s30, v175
	v_mul_f32_e32 v176, s30, v176
	v_mul_f32_e32 v177, s30, v177
	v_fmac_f32_e32 v90, v174, v158
	v_fmac_f32_e32 v91, v175, v159
	v_fmac_f32_e32 v92, v176, v160
	v_fmac_f32_e32 v93, v177, v161
	global_store_dwordx4 v144, v[90:93], s[6:7]
	v_lshlrev_b32_e32 v178, 16, v112
	v_and_b32_e32 v179, 0xffff0000, v112
	v_lshlrev_b32_e32 v180, 16, v113
	v_and_b32_e32 v181, 0xffff0000, v113
	v_mul_f32_e32 v178, s31, v178
	v_mul_f32_e32 v179, s31, v179
	v_mul_f32_e32 v180, s31, v180
	v_mul_f32_e32 v181, s31, v181
	v_fmac_f32_e32 v94, v178, v158
	v_fmac_f32_e32 v95, v179, v159
	v_fmac_f32_e32 v96, v180, v160
	v_fmac_f32_e32 v97, v181, v161
	global_store_dwordx4 v145, v[94:97], s[6:7]
	s_lshl_b32 s22, s86, 16
	s_add_u32 s6, s6, s22
	s_addc_u32 s7, s7, 0
	s_add_i32 s20, s20, s86
	s_cmpk_lt_u32 s20, 0x1000
	s_cbranch_scc0 .LBB0_461
	s_branch .Lr2c_body0
	s_branch .LBB0_461
	s_nop 0
	s_nop 0
	s_nop 0
	s_nop 0
	s_nop 0
	s_nop 0
	s_nop 0
	s_nop 0
	s_nop 0
	s_nop 0
	s_nop 0
	s_nop 0
	s_nop 0
	s_nop 0
	s_nop 0
	s_nop 0
	s_nop 0
	s_nop 0
	s_nop 0
	s_nop 0
	s_nop 0
	s_nop 0
	s_nop 0
	s_nop 0
	s_nop 0
	s_nop 0
	s_nop 0
	s_nop 0
	s_nop 0
